# as version 63 plus sample-row 64x64 GEMM loops prefetch global loads two loop iterations ahead (second staging register set, loop body unrolled twice)
# speedup vs baseline: 1.0024x; 1.0024x over previous
; #define LAS __attribute__((address_space(3)))
; #define LDS_BARRIER() asm volatile("s_waitcnt lgkmcnt(0)\n\ts_barrier" ::: "memory")
; #define MFMA16(a, b, c) __builtin_amdgcn_mfma_f32_16x16x32_bf16((a), (b), (c), 0, 0, 0)
; __device__ __forceinline__ void srg_phase(LAS unsigned char* L, const bf16* Aop, const bf16* Bt, const int K, bf16* xb, float* rowss, const float scale, const bool fin, const int G, const int tid) {
;     ...
;     for (int tile = blockIdx.x; tile < 256; tile += G) {
;         const int tm = tile >> 4, tn = tile & 15;
;         const bf16* ag = Aop + (size_t)(MP + 64 * tm + lr) * K + lc;
;         const bf16* bg = Bt + (size_t)(64 * tn + lr) * K + lc;
;         f32x4 acc0 = {0.f, 0.f, 0.f, 0.f}, acc1 = acc0;
;         v4u ra[2][2], rb[2][2];
; #pragma unroll
;         for (int i = 0; i < 2; ++i) { ra[i][0] = *(const v4u*)(ag + i * 128); ra[i][1] = *(const v4u*)(ag + i * 128 + 64); rb[i][0] = *(const v4u*)(bg + i * 128); rb[i][1] = *(const v4u*)(bg + i * 128 + 64); }
;         LAS unsigned char* wr0 = L + lr * 272 + lc * 2;
;         const LAS unsigned char* fa = L + (16 * wm + r16) * 272 + (8 * q) * 2;
;         const LAS unsigned char* fb = L + 17408 + (32 * wn + r16) * 272 + (8 * q) * 2;
; #pragma unroll 1
;         for (int t = 0; t < nt; t += 2) {
; #pragma unroll
;             for (int i = 0; i < 2; ++i) {
;                 LAS unsigned char* wb_ = wr0 + i * 34816;
;                 *(LAS v4u*)(wb_) = ra[i][0]; *(LAS v4u*)(wb_ + 128) = ra[i][1]; *(LAS v4u*)(wb_ + 17408) = rb[i][0]; *(LAS v4u*)(wb_ + 17408 + 128) = rb[i][1];
;                 { const int tn2 = (t + 2 + i < nt) ? t + 2 + i : i; const bf16* a2 = ag + (size_t)tn2 * 128; const bf16* b2 = bg + (size_t)tn2 * 128;
;                   ra[i][0] = *(const v4u*)a2; ra[i][1] = *(const v4u*)(a2 + 64); rb[i][0] = *(const v4u*)b2; rb[i][1] = *(const v4u*)(b2 + 64); }
;                 LDS_BARRIER();
; #pragma unroll
;                 for (int ks = 0; ks < 4; ++ks) {
;                     const bf16x8 af = frag16(fa + i * 34816 + ks * 64), b0 = frag16(fb + i * 34816 + ks * 64), b1 = frag16(fb + i * 34816 + 16 * 272 + ks * 64);
;                     acc0 = MFMA16(b0, af, acc0); acc1 = MFMA16(b1, af, acc1);
;                 }
;             }
;         }
.LBB0_138:
	s_lshl_b32 s0, s11, 2
	s_andn2_b32 s0, s0, 63
	s_addk_i32 s0, 0x4000
	v_add_u32_e32 v6, s0, v5
	s_lshl_b32 s1, s11, 6
	v_mad_i64_i32 v[6:7], s[12:13], v6, s3, 0
	s_and_b32 s1, s1, 0x3c0
	v_lshl_add_u64 v[50:51], v[6:7], 1, v[46:47]
	v_add_u32_e32 v6, s1, v5
	v_mad_i64_i32 v[6:7], s[12:13], v6, s3, 0
	v_lshl_add_u64 v[52:53], v[6:7], 1, v[48:49]
	global_load_dwordx4 v[18:21], v[50:51], off
	s_waitcnt lgkmcnt(0)
	global_load_dwordx4 v[14:17], v[50:51], off offset:128
	global_load_dwordx4 v[10:13], v[52:53], off
	global_load_dwordx4 v[6:9], v[52:53], off offset:128
	global_load_dwordx4 v[26:29], v[50:51], off offset:256
	global_load_dwordx4 v[30:33], v[50:51], off offset:384
	global_load_dwordx4 v[22:25], v[52:53], off offset:256
	global_load_dwordx4 v[34:37], v[52:53], off offset:384
	global_load_dwordx4 v[152:155], v[50:51], off offset:512
	global_load_dwordx4 v[148:151], v[50:51], off offset:640
	global_load_dwordx4 v[144:147], v[52:53], off offset:512
	global_load_dwordx4 v[140:143], v[52:53], off offset:640
	global_load_dwordx4 v[160:163], v[50:51], off offset:768
	global_load_dwordx4 v[164:167], v[50:51], off offset:896
	global_load_dwordx4 v[156:159], v[52:53], off offset:768
	global_load_dwordx4 v[168:171], v[52:53], off offset:896
	v_mov_b32_e32 v38, 0
	s_mov_b32 s12, 3
	v_mov_b32_e32 v39, v38
	v_mov_b32_e32 v40, v38
	v_mov_b32_e32 v41, v38
	v_mov_b32_e32 v42, v38
	v_mov_b32_e32 v43, v38
	v_mov_b32_e32 v44, v38
	v_mov_b32_e32 v45, v38
.LBB0_139:
	s_add_i32 s13, s12, -1
	s_cmp_lt_u32 s13, s10
	s_cselect_b64 s[14:15], -1, 0
	s_and_b64 vcc, s[14:15], exec
	s_add_i32 s13, s12, 1
	s_cmp_lt_u32 s13, s10
	s_cselect_b32 s62, s13, 0
	s_lshl_b64 s[14:15], s[62:63], 8
	s_waitcnt vmcnt(12)
	ds_write_b128 v56, v[18:21]
	ds_write_b128 v56, v[14:17] offset:128
	ds_write_b128 v56, v[10:13] offset:17408
	ds_write_b128 v56, v[6:9] offset:17536
	v_lshl_add_u64 v[6:7], v[50:51], 0, s[14:15]
	v_lshl_add_u64 v[8:9], v[52:53], 0, s[14:15]
	global_load_dwordx4 v[18:21], v[6:7], off
	global_load_dwordx4 v[14:17], v[6:7], off offset:128
	global_load_dwordx4 v[10:13], v[8:9], off
	s_nop 0
	global_load_dwordx4 v[6:9], v[8:9], off offset:128
	s_waitcnt lgkmcnt(0)
	s_barrier
	ds_read_b128 v[60:63], v57
	ds_read_b128 v[64:67], v58 offset:17408
	ds_read_b128 v[68:71], v58 offset:21760
	s_waitcnt lgkmcnt(1)
	v_mfma_f32_16x16x32_bf16 v[38:41], v[64:67], v[60:63], v[38:41]
	s_add_i32 s13, s12, 2
	s_cmp_lt_u32 s13, s10
	s_cselect_b32 s62, s13, 1
	s_lshl_b64 s[14:15], s[62:63], 8
	s_waitcnt lgkmcnt(0)
	v_mfma_f32_16x16x32_bf16 v[42:45], v[68:71], v[60:63], v[42:45]
	ds_read_b128 v[60:63], v57 offset:64
	ds_read_b128 v[64:67], v58 offset:17472
	ds_read_b128 v[68:71], v58 offset:21824
	s_add_i32 s12, s12, 2
	s_waitcnt lgkmcnt(1)
	v_mfma_f32_16x16x32_bf16 v[38:41], v[64:67], v[60:63], v[38:41]
	s_waitcnt lgkmcnt(0)
	v_mfma_f32_16x16x32_bf16 v[42:45], v[68:71], v[60:63], v[42:45]
	ds_read_b128 v[60:63], v57 offset:128
	ds_read_b128 v[64:67], v58 offset:17536
	ds_read_b128 v[68:71], v58 offset:21888
	s_waitcnt lgkmcnt(1)
	v_mfma_f32_16x16x32_bf16 v[38:41], v[64:67], v[60:63], v[38:41]
	s_waitcnt lgkmcnt(0)
	v_mfma_f32_16x16x32_bf16 v[42:45], v[68:71], v[60:63], v[42:45]
	ds_read_b128 v[60:63], v57 offset:192
	ds_read_b128 v[64:67], v58 offset:17600
	ds_read_b128 v[68:71], v58 offset:21952
	s_waitcnt vmcnt(12)
	ds_write_b128 v56, v[26:29] offset:34816
	ds_write_b128 v56, v[30:33] offset:34944
	ds_write_b128 v56, v[22:25] offset:52224
	ds_write_b128 v56, v[34:37] offset:52352
	v_lshl_add_u64 v[22:23], v[50:51], 0, s[14:15]
	v_lshl_add_u64 v[34:35], v[52:53], 0, s[14:15]
	global_load_dwordx4 v[26:29], v[22:23], off
	global_load_dwordx4 v[30:33], v[22:23], off offset:128
	s_nop 0
	global_load_dwordx4 v[22:25], v[34:35], off
	s_nop 0
	global_load_dwordx4 v[34:37], v[34:35], off offset:128
	s_waitcnt lgkmcnt(0)
	s_barrier
	s_waitcnt lgkmcnt(5)
	v_mfma_f32_16x16x32_bf16 v[38:41], v[64:67], v[60:63], v[38:41]
	s_waitcnt lgkmcnt(4)
	v_mfma_f32_16x16x32_bf16 v[42:45], v[68:71], v[60:63], v[42:45]
	ds_read_b128 v[60:63], v57 offset:34816
	ds_read_b128 v[64:67], v58 offset:52224
	ds_read_b128 v[68:71], v58 offset:56576
	s_waitcnt lgkmcnt(1)
	v_mfma_f32_16x16x32_bf16 v[38:41], v[64:67], v[60:63], v[38:41]
	s_waitcnt lgkmcnt(0)
	v_mfma_f32_16x16x32_bf16 v[42:45], v[68:71], v[60:63], v[42:45]
	ds_read_b128 v[60:63], v57 offset:34880
	ds_read_b128 v[64:67], v58 offset:52288
	ds_read_b128 v[68:71], v58 offset:56640
	s_waitcnt lgkmcnt(1)
	v_mfma_f32_16x16x32_bf16 v[38:41], v[64:67], v[60:63], v[38:41]
	s_waitcnt lgkmcnt(0)
	v_mfma_f32_16x16x32_bf16 v[42:45], v[68:71], v[60:63], v[42:45]
	ds_read_b128 v[60:63], v57 offset:34944
	ds_read_b128 v[64:67], v58 offset:52352
	ds_read_b128 v[68:71], v58 offset:56704
	s_waitcnt lgkmcnt(1)
	v_mfma_f32_16x16x32_bf16 v[38:41], v[64:67], v[60:63], v[38:41]
	s_waitcnt lgkmcnt(0)
	v_mfma_f32_16x16x32_bf16 v[42:45], v[68:71], v[60:63], v[42:45]
	ds_read_b128 v[60:63], v57 offset:35008
	ds_read_b128 v[64:67], v58 offset:52416
	ds_read_b128 v[68:71], v58 offset:56768
	s_waitcnt lgkmcnt(1)
	v_mfma_f32_16x16x32_bf16 v[38:41], v[64:67], v[60:63], v[38:41]
	s_waitcnt lgkmcnt(0)
	v_mfma_f32_16x16x32_bf16 v[42:45], v[68:71], v[60:63], v[42:45]
	s_cbranch_vccz .Lsrg_exit_a
	s_add_i32 s13, s12, -1
	s_cmp_lt_u32 s13, s10
	s_cselect_b64 s[14:15], -1, 0
	s_and_b64 vcc, s[14:15], exec
	s_add_i32 s13, s12, 1
	s_cmp_lt_u32 s13, s10
	s_cselect_b32 s62, s13, 0
	s_lshl_b64 s[14:15], s[62:63], 8
	s_waitcnt vmcnt(12)
	ds_write_b128 v56, v[152:155]
	ds_write_b128 v56, v[148:151] offset:128
	ds_write_b128 v56, v[144:147] offset:17408
	ds_write_b128 v56, v[140:143] offset:17536
	v_lshl_add_u64 v[140:141], v[50:51], 0, s[14:15]
	v_lshl_add_u64 v[142:143], v[52:53], 0, s[14:15]
	global_load_dwordx4 v[152:155], v[140:141], off
	global_load_dwordx4 v[148:151], v[140:141], off offset:128
	global_load_dwordx4 v[144:147], v[142:143], off
	s_nop 0
	global_load_dwordx4 v[140:143], v[142:143], off offset:128
	s_waitcnt lgkmcnt(0)
	s_barrier
; #define LAS __attribute__((address_space(3)))
; #define LDS_BARRIER() asm volatile("s_waitcnt lgkmcnt(0)\n\ts_barrier" ::: "memory")
; __device__ __forceinline__ void srg_phase(LAS unsigned char* L, const bf16* Aop, const bf16* Bt, const int K, bf16* xb, float* rowss, const float scale, const bool fin, const int G, const int tid) {
;     ...
;         for (int t = 0; t < nt; t += 2) {
; #pragma unroll
;             for (int i = 0; i < 2; ++i) {
;                 LAS unsigned char* wb_ = wr0 + i * 34816;
;                 *(LAS v4u*)(wb_) = ra[i][0]; *(LAS v4u*)(wb_ + 128) = ra[i][1]; *(LAS v4u*)(wb_ + 17408) = rb[i][0]; *(LAS v4u*)(wb_ + 17408 + 128) = rb[i][1];
;                 { const int tn2 = (t + 2 + i < nt) ? t + 2 + i : i; const bf16* a2 = ag + (size_t)tn2 * 128; const bf16* b2 = bg + (size_t)tn2 * 128;
;                   ra[i][0] = *(const v4u*)a2; ra[i][1] = *(const v4u*)(a2 + 64); rb[i][0] = *(const v4u*)b2; rb[i][1] = *(const v4u*)(b2 + 64); }
;                 LDS_BARRIER();
; #pragma unroll
;                 for (int ks = 0; ks < 4; ++ks) {
;                     const bf16x8 af = frag16(fa + i * 34816 + ks * 64), b0 = frag16(fb + i * 34816 + ks * 64), b1 = frag16(fb + i * 34816 + 16 * 272 + ks * 64);
;                     acc0 = MFMA16(b0, af, acc0); acc1 = MFMA16(b1, af, acc1);
;                 }
;             }
;         }
;         {
;             const int row = MP + 64 * tm + 16 * wm + r16, col0 = 64 * tn + 32 * wn + 4 * q;
;             bf16* px = xb + (size_t)row * D + col0;
;             const v2u xa = *(const v2u*)px, xc = *(const v2u*)(px + 16);
;             const float a0 = __builtin_bit_cast(float, xa.x << 16) + acc0[0] * scale, a1 = __builtin_bit_cast(float, xa.x & 0xffff0000u) + acc0[1] * scale, a2 = __builtin_bit_cast(float, xa.y << 16) + acc0[2] * scale, a3 = __builtin_bit_cast(float, xa.y & 0xffff0000u) + acc0[3] * scale;
;             const float b0 = __builtin_bit_cast(float, xc.x << 16) + acc1[0] * scale, b1 = __builtin_bit_cast(float, xc.x & 0xffff0000u) + acc1[1] * scale, b2 = __builtin_bit_cast(float, xc.y << 16) + acc1[2] * scale, b3 = __builtin_bit_cast(float, xc.y & 0xffff0000u) + acc1[3] * scale;
;             v2u wa, wb; wa.x = cvtpk(a0, a1); wa.y = cvtpk(a2, a3); wb.x = cvtpk(b0, b1); wb.y = cvtpk(b2, b3);
;             *(v2u*)px = wa; *(v2u*)(px + 16) = wb;
;             float ss = 0.f;
; #pragma unroll
	ds_read_b128 v[60:63], v57
	ds_read_b128 v[64:67], v58 offset:17408
	ds_read_b128 v[68:71], v58 offset:21760
	s_waitcnt lgkmcnt(1)
	v_mfma_f32_16x16x32_bf16 v[38:41], v[64:67], v[60:63], v[38:41]
	s_add_i32 s13, s12, 2
	s_cmp_lt_u32 s13, s10
	s_cselect_b32 s62, s13, 1
	s_lshl_b64 s[14:15], s[62:63], 8
	s_waitcnt lgkmcnt(0)
	v_mfma_f32_16x16x32_bf16 v[42:45], v[68:71], v[60:63], v[42:45]
	ds_read_b128 v[60:63], v57 offset:64
	ds_read_b128 v[64:67], v58 offset:17472
	ds_read_b128 v[68:71], v58 offset:21824
	s_add_i32 s12, s12, 2
	s_waitcnt lgkmcnt(1)
	v_mfma_f32_16x16x32_bf16 v[38:41], v[64:67], v[60:63], v[38:41]
	s_waitcnt lgkmcnt(0)
	v_mfma_f32_16x16x32_bf16 v[42:45], v[68:71], v[60:63], v[42:45]
	ds_read_b128 v[60:63], v57 offset:128
	ds_read_b128 v[64:67], v58 offset:17536
	ds_read_b128 v[68:71], v58 offset:21888
	s_waitcnt lgkmcnt(1)
	v_mfma_f32_16x16x32_bf16 v[38:41], v[64:67], v[60:63], v[38:41]
	s_waitcnt lgkmcnt(0)
	v_mfma_f32_16x16x32_bf16 v[42:45], v[68:71], v[60:63], v[42:45]
	ds_read_b128 v[60:63], v57 offset:192
	ds_read_b128 v[64:67], v58 offset:17600
	ds_read_b128 v[68:71], v58 offset:21952
	s_waitcnt vmcnt(12)
	ds_write_b128 v56, v[160:163] offset:34816
	ds_write_b128 v56, v[164:167] offset:34944
	ds_write_b128 v56, v[156:159] offset:52224
	ds_write_b128 v56, v[168:171] offset:52352
	v_lshl_add_u64 v[156:157], v[50:51], 0, s[14:15]
	v_lshl_add_u64 v[168:169], v[52:53], 0, s[14:15]
	global_load_dwordx4 v[160:163], v[156:157], off
	global_load_dwordx4 v[164:167], v[156:157], off offset:128
	s_nop 0
	global_load_dwordx4 v[156:159], v[168:169], off
	s_nop 0
	global_load_dwordx4 v[168:171], v[168:169], off offset:128
	s_waitcnt lgkmcnt(0)
	s_barrier
	s_waitcnt lgkmcnt(5)
	v_mfma_f32_16x16x32_bf16 v[38:41], v[64:67], v[60:63], v[38:41]
	s_waitcnt lgkmcnt(4)
	v_mfma_f32_16x16x32_bf16 v[42:45], v[68:71], v[60:63], v[42:45]
	ds_read_b128 v[60:63], v57 offset:34816
	ds_read_b128 v[64:67], v58 offset:52224
	ds_read_b128 v[68:71], v58 offset:56576
	s_waitcnt lgkmcnt(1)
	v_mfma_f32_16x16x32_bf16 v[38:41], v[64:67], v[60:63], v[38:41]
	s_waitcnt lgkmcnt(0)
	v_mfma_f32_16x16x32_bf16 v[42:45], v[68:71], v[60:63], v[42:45]
	ds_read_b128 v[60:63], v57 offset:34880
	ds_read_b128 v[64:67], v58 offset:52288
	ds_read_b128 v[68:71], v58 offset:56640
	s_waitcnt lgkmcnt(1)
	v_mfma_f32_16x16x32_bf16 v[38:41], v[64:67], v[60:63], v[38:41]
	s_waitcnt lgkmcnt(0)
	v_mfma_f32_16x16x32_bf16 v[42:45], v[68:71], v[60:63], v[42:45]
	ds_read_b128 v[60:63], v57 offset:34944
	ds_read_b128 v[64:67], v58 offset:52352
	ds_read_b128 v[68:71], v58 offset:56704
	s_waitcnt lgkmcnt(1)
	v_mfma_f32_16x16x32_bf16 v[38:41], v[64:67], v[60:63], v[38:41]
	s_waitcnt lgkmcnt(0)
	v_mfma_f32_16x16x32_bf16 v[42:45], v[68:71], v[60:63], v[42:45]
	ds_read_b128 v[60:63], v57 offset:35008
	ds_read_b128 v[64:67], v58 offset:52416
	ds_read_b128 v[68:71], v58 offset:56768
	s_waitcnt lgkmcnt(1)
	v_mfma_f32_16x16x32_bf16 v[38:41], v[64:67], v[60:63], v[38:41]
	s_waitcnt lgkmcnt(0)
	v_mfma_f32_16x16x32_bf16 v[42:45], v[68:71], v[60:63], v[42:45]
	s_cbranch_vccnz .LBB0_139
.Lsrg_exit_a:
	s_waitcnt vmcnt(4)
	v_add_u32_e32 v6, s0, v54
	v_ashrrev_i32_e32 v7, 31, v6
	v_or_b32_e32 v10, s1, v55
	v_lshlrev_b64 v[8:9], 11, v[6:7]
	v_lshl_add_u64 v[8:9], s[84:85], 0, v[8:9]
	v_lshlrev_b32_e32 v10, 1, v10
	v_mov_b32_e32 v11, v4
	v_lshl_add_u64 v[8:9], v[8:9], 0, v[10:11]
	global_load_dwordx2 v[10:11], v[8:9], off
	global_load_dwordx2 v[12:13], v[8:9], off offset:32
	s_waitcnt vmcnt(1)
	v_lshlrev_b32_e32 v14, 16, v10
	v_and_b32_e32 v15, 0xffff0000, v10
	v_lshlrev_b32_e32 v10, 16, v11
	v_and_b32_e32 v11, 0xffff0000, v11
	v_pk_fma_f32 v[14:15], v[2:3], v[38:39], v[14:15]
	v_pk_fma_f32 v[10:11], v[2:3], v[40:41], v[10:11]
	s_waitcnt vmcnt(0)
	v_lshlrev_b32_e32 v16, 16, v12
	v_and_b32_e32 v17, 0xffff0000, v12
	v_lshlrev_b32_e32 v12, 16, v13
	v_and_b32_e32 v13, 0xffff0000, v13
	v_pk_fma_f32 v[16:17], v[2:3], v[42:43], v[16:17]
	v_pk_fma_f32 v[12:13], v[2:3], v[44:45], v[12:13]
	v_cvt_pk_bf16_f32 v14, v14, v15
	v_cvt_pk_bf16_f32 v15, v10, v11
	v_cvt_pk_bf16_f32 v10, v16, v17
	v_cvt_pk_bf16_f32 v11, v12, v13
	global_store_dwordx2 v[8:9], v[14:15], off
	global_store_dwordx2 v[8:9], v[10:11], off offset:32
	v_and_b32_e32 v9, 0xffff0000, v14
	v_lshlrev_b32_e32 v8, 16, v14
	v_lshlrev_b32_e32 v12, 16, v10
	v_and_b32_e32 v10, 0xffff0000, v10
	v_mul_f32_e32 v9, v9, v9
	v_fmac_f32_e32 v9, v8, v8
	v_mul_f32_e32 v8, v10, v10
	v_fmac_f32_e32 v8, v12, v12
	v_and_b32_e32 v10, 0xffff0000, v15
	v_add_f32_e32 v8, v9, v8
	v_lshlrev_b32_e32 v9, 16, v15
	v_lshlrev_b32_e32 v12, 16, v11
	v_and_b32_e32 v11, 0xffff0000, v11
	v_mul_f32_e32 v10, v10, v10
	v_fmac_f32_e32 v10, v9, v9
	v_mul_f32_e32 v9, v11, v11
	v_fmac_f32_e32 v9, v12, v12
	v_add_f32_e32 v9, v10, v9
	v_and_b32_e32 v10, 64, v232
	v_add_f32_e32 v8, v8, v9
	v_xor_b32_e32 v9, 16, v232
	v_add_u32_e32 v10, 64, v10
	v_cmp_lt_i32_e32 vcc, v9, v10
	s_nop 1
	v_cndmask_b32_e32 v9, v232, v9, vcc
	v_lshlrev_b32_e32 v9, 2, v9
	ds_bpermute_b32 v9, v9, v8
	s_waitcnt lgkmcnt(0)
	v_add_f32_e32 v8, v8, v9
	v_xor_b32_e32 v9, 32, v232
	v_cmp_lt_i32_e32 vcc, v9, v10
	s_nop 1
	v_cndmask_b32_e32 v9, v232, v9, vcc
	v_lshlrev_b32_e32 v9, 2, v9
	ds_bpermute_b32 v9, v9, v8
	s_and_saveexec_b64 s[0:1], s[38:39]
	s_cbranch_execz .LBB0_137
	s_waitcnt lgkmcnt(0)
	v_add_f32_e32 v8, v8, v9
	v_lshl_add_u64 v[6:7], v[6:7], 2, s[8:9]
	global_atomic_add_f32 v[6:7], v8, off
	s_branch .LBB0_137

; #define LAS __attribute__((address_space(3)))
; #define LDS_BARRIER() asm volatile("s_waitcnt lgkmcnt(0)\n\ts_barrier" ::: "memory")
; #define MFMA16(a, b, c) __builtin_amdgcn_mfma_f32_16x16x32_bf16((a), (b), (c), 0, 0, 0)
; __device__ __forceinline__ void srg_phase(LAS unsigned char* L, const bf16* Aop, const bf16* Bt, const int K, bf16* xb, float* rowss, const float scale, const bool fin, const int G, const int tid) {
;     ...
;     for (int tile = blockIdx.x; tile < 256; tile += G) {
;         const int tm = tile >> 4, tn = tile & 15;
;         const bf16* ag = Aop + (size_t)(MP + 64 * tm + lr) * K + lc;
;         const bf16* bg = Bt + (size_t)(64 * tn + lr) * K + lc;
;         f32x4 acc0 = {0.f, 0.f, 0.f, 0.f}, acc1 = acc0;
;         v4u ra[2][2], rb[2][2];
; #pragma unroll
;         for (int i = 0; i < 2; ++i) { ra[i][0] = *(const v4u*)(ag + i * 128); ra[i][1] = *(const v4u*)(ag + i * 128 + 64); rb[i][0] = *(const v4u*)(bg + i * 128); rb[i][1] = *(const v4u*)(bg + i * 128 + 64); }
;         LAS unsigned char* wr0 = L + lr * 272 + lc * 2;
;         const LAS unsigned char* fa = L + (16 * wm + r16) * 272 + (8 * q) * 2;
;         const LAS unsigned char* fb = L + 17408 + (32 * wn + r16) * 272 + (8 * q) * 2;
; #pragma unroll 1
;         for (int t = 0; t < nt; t += 2) {
; #pragma unroll
;             for (int i = 0; i < 2; ++i) {
;                 LAS unsigned char* wb_ = wr0 + i * 34816;
;                 *(LAS v4u*)(wb_) = ra[i][0]; *(LAS v4u*)(wb_ + 128) = ra[i][1]; *(LAS v4u*)(wb_ + 17408) = rb[i][0]; *(LAS v4u*)(wb_ + 17408 + 128) = rb[i][1];
;                 { const int tn2 = (t + 2 + i < nt) ? t + 2 + i : i; const bf16* a2 = ag + (size_t)tn2 * 128; const bf16* b2 = bg + (size_t)tn2 * 128;
;                   ra[i][0] = *(const v4u*)a2; ra[i][1] = *(const v4u*)(a2 + 64); rb[i][0] = *(const v4u*)b2; rb[i][1] = *(const v4u*)(b2 + 64); }
;                 LDS_BARRIER();
; #pragma unroll
;                 for (int ks = 0; ks < 4; ++ks) {
;                     const bf16x8 af = frag16(fa + i * 34816 + ks * 64), b0 = frag16(fb + i * 34816 + ks * 64), b1 = frag16(fb + i * 34816 + 16 * 272 + ks * 64);
;                     acc0 = MFMA16(b0, af, acc0); acc1 = MFMA16(b1, af, acc1);
;                 }
;             }
;         }
.LBB0_192:
	s_lshl_b32 s0, s11, 2
	s_andn2_b32 s0, s0, 63
	s_addk_i32 s0, 0x4000
	v_add_u32_e32 v6, s0, v54
	s_lshl_b32 s1, s11, 6
	v_mad_i64_i32 v[6:7], s[12:13], v6, s3, 0
	s_and_b32 s1, s1, 0x3c0
	v_lshl_add_u64 v[50:51], v[6:7], 1, v[46:47]
	v_add_u32_e32 v6, s1, v54
	v_mad_i64_i32 v[6:7], s[12:13], v6, s3, 0
	v_lshl_add_u64 v[52:53], v[6:7], 1, v[48:49]
	global_load_dwordx4 v[18:21], v[50:51], off
	s_waitcnt lgkmcnt(0)
	global_load_dwordx4 v[14:17], v[50:51], off offset:128
	global_load_dwordx4 v[10:13], v[52:53], off
	global_load_dwordx4 v[6:9], v[52:53], off offset:128
	global_load_dwordx4 v[26:29], v[50:51], off offset:256
	global_load_dwordx4 v[30:33], v[50:51], off offset:384
	global_load_dwordx4 v[22:25], v[52:53], off offset:256
	global_load_dwordx4 v[34:37], v[52:53], off offset:384
	global_load_dwordx4 v[152:155], v[50:51], off offset:512
	global_load_dwordx4 v[148:151], v[50:51], off offset:640
	global_load_dwordx4 v[144:147], v[52:53], off offset:512
	global_load_dwordx4 v[140:143], v[52:53], off offset:640
	global_load_dwordx4 v[160:163], v[50:51], off offset:768
	global_load_dwordx4 v[164:167], v[50:51], off offset:896
	global_load_dwordx4 v[156:159], v[52:53], off offset:768
	global_load_dwordx4 v[168:171], v[52:53], off offset:896
	v_mov_b32_e32 v38, 0
	s_mov_b32 s12, 3
	v_mov_b32_e32 v39, v38
	v_mov_b32_e32 v40, v38
	v_mov_b32_e32 v41, v38
	v_mov_b32_e32 v42, v38
	v_mov_b32_e32 v43, v38
	v_mov_b32_e32 v44, v38
	v_mov_b32_e32 v45, v38
.LBB0_193:
	s_add_i32 s13, s12, -1
	s_cmp_lt_u32 s13, s10
	s_cselect_b64 s[14:15], -1, 0
	s_and_b64 vcc, s[14:15], exec
	s_add_i32 s13, s12, 1
	s_cmp_lt_u32 s13, s10
	s_cselect_b32 s62, s13, 0
	s_lshl_b64 s[14:15], s[62:63], 8
	s_waitcnt vmcnt(12)
	ds_write_b128 v57, v[18:21]
	ds_write_b128 v57, v[14:17] offset:128
	ds_write_b128 v57, v[10:13] offset:17408
	ds_write_b128 v57, v[6:9] offset:17536
	v_lshl_add_u64 v[6:7], v[50:51], 0, s[14:15]
	v_lshl_add_u64 v[8:9], v[52:53], 0, s[14:15]
	global_load_dwordx4 v[18:21], v[6:7], off
	global_load_dwordx4 v[14:17], v[6:7], off offset:128
	global_load_dwordx4 v[10:13], v[8:9], off
	s_nop 0
	global_load_dwordx4 v[6:9], v[8:9], off offset:128
	s_waitcnt lgkmcnt(0)
	s_barrier
	ds_read_b128 v[60:63], v58
	ds_read_b128 v[64:67], v5 offset:17408
	ds_read_b128 v[68:71], v5 offset:21760
	s_waitcnt lgkmcnt(1)
	v_mfma_f32_16x16x32_bf16 v[38:41], v[64:67], v[60:63], v[38:41]
	s_add_i32 s13, s12, 2
	s_cmp_lt_u32 s13, s10
	s_cselect_b32 s62, s13, 1
	s_lshl_b64 s[14:15], s[62:63], 8
	s_waitcnt lgkmcnt(0)
	v_mfma_f32_16x16x32_bf16 v[42:45], v[68:71], v[60:63], v[42:45]
	ds_read_b128 v[60:63], v58 offset:64
	ds_read_b128 v[64:67], v5 offset:17472
	ds_read_b128 v[68:71], v5 offset:21824
	s_add_i32 s12, s12, 2
	s_waitcnt lgkmcnt(1)
	v_mfma_f32_16x16x32_bf16 v[38:41], v[64:67], v[60:63], v[38:41]
	s_waitcnt lgkmcnt(0)
	v_mfma_f32_16x16x32_bf16 v[42:45], v[68:71], v[60:63], v[42:45]
	ds_read_b128 v[60:63], v58 offset:128
	ds_read_b128 v[64:67], v5 offset:17536
	ds_read_b128 v[68:71], v5 offset:21888
	s_waitcnt lgkmcnt(1)
	v_mfma_f32_16x16x32_bf16 v[38:41], v[64:67], v[60:63], v[38:41]
	s_waitcnt lgkmcnt(0)
	v_mfma_f32_16x16x32_bf16 v[42:45], v[68:71], v[60:63], v[42:45]
	ds_read_b128 v[60:63], v58 offset:192
	ds_read_b128 v[64:67], v5 offset:17600
	ds_read_b128 v[68:71], v5 offset:21952
	s_waitcnt vmcnt(12)
	ds_write_b128 v57, v[26:29] offset:34816
	ds_write_b128 v57, v[30:33] offset:34944
	ds_write_b128 v57, v[22:25] offset:52224
	ds_write_b128 v57, v[34:37] offset:52352
	v_lshl_add_u64 v[22:23], v[50:51], 0, s[14:15]
	v_lshl_add_u64 v[34:35], v[52:53], 0, s[14:15]
	global_load_dwordx4 v[26:29], v[22:23], off
	global_load_dwordx4 v[30:33], v[22:23], off offset:128
	s_nop 0
	global_load_dwordx4 v[22:25], v[34:35], off
	s_nop 0
	global_load_dwordx4 v[34:37], v[34:35], off offset:128
	s_waitcnt lgkmcnt(0)
	s_barrier
	s_waitcnt lgkmcnt(5)
	v_mfma_f32_16x16x32_bf16 v[38:41], v[64:67], v[60:63], v[38:41]
	s_waitcnt lgkmcnt(4)
	v_mfma_f32_16x16x32_bf16 v[42:45], v[68:71], v[60:63], v[42:45]
	ds_read_b128 v[60:63], v58 offset:34816
	ds_read_b128 v[64:67], v5 offset:52224
	ds_read_b128 v[68:71], v5 offset:56576
	s_waitcnt lgkmcnt(1)
	v_mfma_f32_16x16x32_bf16 v[38:41], v[64:67], v[60:63], v[38:41]
	s_waitcnt lgkmcnt(0)
	v_mfma_f32_16x16x32_bf16 v[42:45], v[68:71], v[60:63], v[42:45]
	ds_read_b128 v[60:63], v58 offset:34880
	ds_read_b128 v[64:67], v5 offset:52288
	ds_read_b128 v[68:71], v5 offset:56640
	s_waitcnt lgkmcnt(1)
	v_mfma_f32_16x16x32_bf16 v[38:41], v[64:67], v[60:63], v[38:41]
	s_waitcnt lgkmcnt(0)
	v_mfma_f32_16x16x32_bf16 v[42:45], v[68:71], v[60:63], v[42:45]
	ds_read_b128 v[60:63], v58 offset:34944
	ds_read_b128 v[64:67], v5 offset:52352
	ds_read_b128 v[68:71], v5 offset:56704
	s_waitcnt lgkmcnt(1)
	v_mfma_f32_16x16x32_bf16 v[38:41], v[64:67], v[60:63], v[38:41]
	s_waitcnt lgkmcnt(0)
	v_mfma_f32_16x16x32_bf16 v[42:45], v[68:71], v[60:63], v[42:45]
	ds_read_b128 v[60:63], v58 offset:35008
	ds_read_b128 v[64:67], v5 offset:52416
	ds_read_b128 v[68:71], v5 offset:56768
	s_waitcnt lgkmcnt(1)
	v_mfma_f32_16x16x32_bf16 v[38:41], v[64:67], v[60:63], v[38:41]
	s_waitcnt lgkmcnt(0)
	v_mfma_f32_16x16x32_bf16 v[42:45], v[68:71], v[60:63], v[42:45]
	s_cbranch_vccz .Lsrg_exit_b
	s_add_i32 s13, s12, -1
	s_cmp_lt_u32 s13, s10
	s_cselect_b64 s[14:15], -1, 0
	s_and_b64 vcc, s[14:15], exec
	s_add_i32 s13, s12, 1
	s_cmp_lt_u32 s13, s10
	s_cselect_b32 s62, s13, 0
	s_lshl_b64 s[14:15], s[62:63], 8
	s_waitcnt vmcnt(12)
	ds_write_b128 v57, v[152:155]
	ds_write_b128 v57, v[148:151] offset:128
	ds_write_b128 v57, v[144:147] offset:17408
	ds_write_b128 v57, v[140:143] offset:17536
	v_lshl_add_u64 v[140:141], v[50:51], 0, s[14:15]
	v_lshl_add_u64 v[142:143], v[52:53], 0, s[14:15]
	global_load_dwordx4 v[152:155], v[140:141], off
	global_load_dwordx4 v[148:151], v[140:141], off offset:128
	global_load_dwordx4 v[144:147], v[142:143], off
	s_nop 0
	global_load_dwordx4 v[140:143], v[142:143], off offset:128
	s_waitcnt lgkmcnt(0)
	s_barrier
; #define LAS __attribute__((address_space(3)))
; #define LDS_BARRIER() asm volatile("s_waitcnt lgkmcnt(0)\n\ts_barrier" ::: "memory")
; __device__ __forceinline__ void srg_phase(LAS unsigned char* L, const bf16* Aop, const bf16* Bt, const int K, bf16* xb, float* rowss, const float scale, const bool fin, const int G, const int tid) {
;     ...
;         for (int t = 0; t < nt; t += 2) {
; #pragma unroll
;             for (int i = 0; i < 2; ++i) {
;                 LAS unsigned char* wb_ = wr0 + i * 34816;
;                 *(LAS v4u*)(wb_) = ra[i][0]; *(LAS v4u*)(wb_ + 128) = ra[i][1]; *(LAS v4u*)(wb_ + 17408) = rb[i][0]; *(LAS v4u*)(wb_ + 17408 + 128) = rb[i][1];
;                 { const int tn2 = (t + 2 + i < nt) ? t + 2 + i : i; const bf16* a2 = ag + (size_t)tn2 * 128; const bf16* b2 = bg + (size_t)tn2 * 128;
;                   ra[i][0] = *(const v4u*)a2; ra[i][1] = *(const v4u*)(a2 + 64); rb[i][0] = *(const v4u*)b2; rb[i][1] = *(const v4u*)(b2 + 64); }
;                 LDS_BARRIER();
; #pragma unroll
;                 for (int ks = 0; ks < 4; ++ks) {
;                     const bf16x8 af = frag16(fa + i * 34816 + ks * 64), b0 = frag16(fb + i * 34816 + ks * 64), b1 = frag16(fb + i * 34816 + 16 * 272 + ks * 64);
;                     acc0 = MFMA16(b0, af, acc0); acc1 = MFMA16(b1, af, acc1);
;                 }
;             }
;         }
;         {
;             const int row = MP + 64 * tm + 16 * wm + r16, col0 = 64 * tn + 32 * wn + 4 * q;
;             bf16* px = xb + (size_t)row * D + col0;
;             const v2u xa = *(const v2u*)px, xc = *(const v2u*)(px + 16);
;             const float a0 = __builtin_bit_cast(float, xa.x << 16) + acc0[0] * scale, a1 = __builtin_bit_cast(float, xa.x & 0xffff0000u) + acc0[1] * scale, a2 = __builtin_bit_cast(float, xa.y << 16) + acc0[2] * scale, a3 = __builtin_bit_cast(float, xa.y & 0xffff0000u) + acc0[3] * scale;
;             const float b0 = __builtin_bit_cast(float, xc.x << 16) + acc1[0] * scale, b1 = __builtin_bit_cast(float, xc.x & 0xffff0000u) + acc1[1] * scale, b2 = __builtin_bit_cast(float, xc.y << 16) + acc1[2] * scale, b3 = __builtin_bit_cast(float, xc.y & 0xffff0000u) + acc1[3] * scale;
;             v2u wa, wb; wa.x = cvtpk(a0, a1); wa.y = cvtpk(a2, a3); wb.x = cvtpk(b0, b1); wb.y = cvtpk(b2, b3);
;             *(v2u*)px = wa; *(v2u*)(px + 16) = wb;
;             float ss = 0.f;
; #pragma unroll
	ds_read_b128 v[60:63], v58
	ds_read_b128 v[64:67], v5 offset:17408
	ds_read_b128 v[68:71], v5 offset:21760
	s_waitcnt lgkmcnt(1)
	v_mfma_f32_16x16x32_bf16 v[38:41], v[64:67], v[60:63], v[38:41]
	s_add_i32 s13, s12, 2
	s_cmp_lt_u32 s13, s10
	s_cselect_b32 s62, s13, 1
	s_lshl_b64 s[14:15], s[62:63], 8
	s_waitcnt lgkmcnt(0)
	v_mfma_f32_16x16x32_bf16 v[42:45], v[68:71], v[60:63], v[42:45]
	ds_read_b128 v[60:63], v58 offset:64
	ds_read_b128 v[64:67], v5 offset:17472
	ds_read_b128 v[68:71], v5 offset:21824
	s_add_i32 s12, s12, 2
	s_waitcnt lgkmcnt(1)
	v_mfma_f32_16x16x32_bf16 v[38:41], v[64:67], v[60:63], v[38:41]
	s_waitcnt lgkmcnt(0)
	v_mfma_f32_16x16x32_bf16 v[42:45], v[68:71], v[60:63], v[42:45]
	ds_read_b128 v[60:63], v58 offset:128
	ds_read_b128 v[64:67], v5 offset:17536
	ds_read_b128 v[68:71], v5 offset:21888
	s_waitcnt lgkmcnt(1)
	v_mfma_f32_16x16x32_bf16 v[38:41], v[64:67], v[60:63], v[38:41]
	s_waitcnt lgkmcnt(0)
	v_mfma_f32_16x16x32_bf16 v[42:45], v[68:71], v[60:63], v[42:45]
	ds_read_b128 v[60:63], v58 offset:192
	ds_read_b128 v[64:67], v5 offset:17600
	ds_read_b128 v[68:71], v5 offset:21952
	s_waitcnt vmcnt(12)
	ds_write_b128 v57, v[160:163] offset:34816
	ds_write_b128 v57, v[164:167] offset:34944
	ds_write_b128 v57, v[156:159] offset:52224
	ds_write_b128 v57, v[168:171] offset:52352
	v_lshl_add_u64 v[156:157], v[50:51], 0, s[14:15]
	v_lshl_add_u64 v[168:169], v[52:53], 0, s[14:15]
	global_load_dwordx4 v[160:163], v[156:157], off
	global_load_dwordx4 v[164:167], v[156:157], off offset:128
	s_nop 0
	global_load_dwordx4 v[156:159], v[168:169], off
	s_nop 0
	global_load_dwordx4 v[168:171], v[168:169], off offset:128
	s_waitcnt lgkmcnt(0)
	s_barrier
	s_waitcnt lgkmcnt(5)
	v_mfma_f32_16x16x32_bf16 v[38:41], v[64:67], v[60:63], v[38:41]
	s_waitcnt lgkmcnt(4)
	v_mfma_f32_16x16x32_bf16 v[42:45], v[68:71], v[60:63], v[42:45]
	ds_read_b128 v[60:63], v58 offset:34816
	ds_read_b128 v[64:67], v5 offset:52224
	ds_read_b128 v[68:71], v5 offset:56576
	s_waitcnt lgkmcnt(1)
	v_mfma_f32_16x16x32_bf16 v[38:41], v[64:67], v[60:63], v[38:41]
	s_waitcnt lgkmcnt(0)
	v_mfma_f32_16x16x32_bf16 v[42:45], v[68:71], v[60:63], v[42:45]
	ds_read_b128 v[60:63], v58 offset:34880
	ds_read_b128 v[64:67], v5 offset:52288
	ds_read_b128 v[68:71], v5 offset:56640
	s_waitcnt lgkmcnt(1)
	v_mfma_f32_16x16x32_bf16 v[38:41], v[64:67], v[60:63], v[38:41]
	s_waitcnt lgkmcnt(0)
	v_mfma_f32_16x16x32_bf16 v[42:45], v[68:71], v[60:63], v[42:45]
	ds_read_b128 v[60:63], v58 offset:34944
	ds_read_b128 v[64:67], v5 offset:52352
	ds_read_b128 v[68:71], v5 offset:56704
	s_waitcnt lgkmcnt(1)
	v_mfma_f32_16x16x32_bf16 v[38:41], v[64:67], v[60:63], v[38:41]
	s_waitcnt lgkmcnt(0)
	v_mfma_f32_16x16x32_bf16 v[42:45], v[68:71], v[60:63], v[42:45]
	ds_read_b128 v[60:63], v58 offset:35008
	ds_read_b128 v[64:67], v5 offset:52416
	ds_read_b128 v[68:71], v5 offset:56768
	s_waitcnt lgkmcnt(1)
	v_mfma_f32_16x16x32_bf16 v[38:41], v[64:67], v[60:63], v[38:41]
	s_waitcnt lgkmcnt(0)
	v_mfma_f32_16x16x32_bf16 v[42:45], v[68:71], v[60:63], v[42:45]
	s_cbranch_vccnz .LBB0_193
.Lsrg_exit_b:
	s_waitcnt vmcnt(4)
	v_add_u32_e32 v6, s0, v55
	v_ashrrev_i32_e32 v7, 31, v6
	v_or_b32_e32 v10, s1, v56
	v_lshlrev_b64 v[8:9], 11, v[6:7]
	v_lshl_add_u64 v[8:9], s[84:85], 0, v[8:9]
	v_lshlrev_b32_e32 v10, 1, v10
	v_mov_b32_e32 v11, v4
	v_lshl_add_u64 v[8:9], v[8:9], 0, v[10:11]
	global_load_dwordx2 v[10:11], v[8:9], off
	global_load_dwordx2 v[12:13], v[8:9], off offset:32
	s_waitcnt vmcnt(1)
	v_lshlrev_b32_e32 v14, 16, v10
	v_and_b32_e32 v15, 0xffff0000, v10
	v_lshlrev_b32_e32 v10, 16, v11
	v_and_b32_e32 v11, 0xffff0000, v11
	v_pk_fma_f32 v[14:15], v[2:3], v[38:39], v[14:15]
	v_pk_fma_f32 v[10:11], v[2:3], v[40:41], v[10:11]
	s_waitcnt vmcnt(0)
	v_lshlrev_b32_e32 v16, 16, v12
	v_and_b32_e32 v17, 0xffff0000, v12
	v_lshlrev_b32_e32 v12, 16, v13
	v_and_b32_e32 v13, 0xffff0000, v13
	v_pk_fma_f32 v[16:17], v[2:3], v[42:43], v[16:17]
	v_pk_fma_f32 v[12:13], v[2:3], v[44:45], v[12:13]
	v_cvt_pk_bf16_f32 v14, v14, v15
	v_cvt_pk_bf16_f32 v15, v10, v11
	v_cvt_pk_bf16_f32 v10, v16, v17
	v_cvt_pk_bf16_f32 v11, v12, v13
	global_store_dwordx2 v[8:9], v[14:15], off
	global_store_dwordx2 v[8:9], v[10:11], off offset:32
	v_and_b32_e32 v9, 0xffff0000, v14
	v_lshlrev_b32_e32 v8, 16, v14
	v_lshlrev_b32_e32 v12, 16, v10
	v_and_b32_e32 v10, 0xffff0000, v10
	v_mul_f32_e32 v9, v9, v9
	v_fmac_f32_e32 v9, v8, v8
	v_mul_f32_e32 v8, v10, v10
	v_fmac_f32_e32 v8, v12, v12
	v_and_b32_e32 v10, 0xffff0000, v15
	v_add_f32_e32 v8, v9, v8
	v_lshlrev_b32_e32 v9, 16, v15
	v_lshlrev_b32_e32 v12, 16, v11
	v_and_b32_e32 v11, 0xffff0000, v11
	v_mul_f32_e32 v10, v10, v10
	v_fmac_f32_e32 v10, v9, v9
	v_mul_f32_e32 v9, v11, v11
	v_fmac_f32_e32 v9, v12, v12
	v_add_f32_e32 v9, v10, v9
	v_and_b32_e32 v10, 64, v232
	v_add_f32_e32 v8, v8, v9
	v_xor_b32_e32 v9, 16, v232
	v_add_u32_e32 v10, 64, v10
	v_cmp_lt_i32_e32 vcc, v9, v10
	s_nop 1
	v_cndmask_b32_e32 v9, v232, v9, vcc
	v_lshlrev_b32_e32 v9, 2, v9
	ds_bpermute_b32 v9, v9, v8
	s_waitcnt lgkmcnt(0)
	v_add_f32_e32 v8, v8, v9
	v_xor_b32_e32 v9, 32, v232
	v_cmp_lt_i32_e32 vcc, v9, v10
	s_nop 1
	v_cndmask_b32_e32 v9, v232, v9, vcc
	v_lshlrev_b32_e32 v9, 2, v9
	ds_bpermute_b32 v9, v9, v8
	s_and_saveexec_b64 s[0:1], s[36:37]
	s_cbranch_execz .LBB0_191
	s_waitcnt lgkmcnt(0)
	v_add_f32_e32 v8, v8, v9
	v_lshl_add_u64 v[6:7], v[6:7], 2, s[8:9]
	global_atomic_add_f32 v[6:7], v8, off
	s_branch .LBB0_191
